# stack4: stack3 + v_pk_mul_f32 split into scalar v_mul_f32 pairs in the two SwiGLU GEMM epilogues
# baseline (speedup 1.0000x reference)
; __device__ __forceinline__ unsigned pk2(float lo, float hi) { f32x2 v = {lo, hi}; bf16x2_t b = __builtin_convertvector(v, bf16x2_t); return __builtin_bit_cast(unsigned, b); }
;     __device__ __forceinline__ void operator()(const AccT& acc, const pg8::Unit& u, int wr, int wc, int fr, int fq) const {
;         const int col = u.pn * 128 + wc * 32 + fq * 8;
; #pragma unroll
;         for (int ai = 0; ai < 2; ++ai)
; #pragma unroll
;             for (int m = 0; m < 4; ++m) {
;                 const int row = u.pm * 256 + ai * 128 + wr * 64 + m * 16 + fr;
;                 float o[8];
; #pragma unroll
;                 for (int n = 0; n < 2; ++n)
; #pragma unroll
;                     for (int j = 0; j < 4; ++j) { const float gt = acc[ai][0][m][n][j], up = acc[ai][1][m][n][j];
;                         const float sg = gt * __builtin_amdgcn_rcpf(1.f + __builtin_amdgcn_exp2f(-gt * 1.4426950408889634f)); o[n * 4 + j] = sg * up; }
;                 u32x4 w; w.x = pk2(o[0], o[1]); w.y = pk2(o[2], o[3]); w.z = pk2(o[4], o[5]); w.w = pk2(o[6], o[7]);
;                 *(u32x4*)(H + (size_t)row * DFF + col) = w;
;             }
.LBB0_585:
	v_mul_f32_e32 v150, 0xbfb8aa3b, v124
	v_mul_f32_e32 v151, 0xbfb8aa3b, v125
	v_exp_f32_e32 v150, v150
	v_exp_f32_e32 v151, v151
	v_lshl_or_b32 v154, s31, 7, v146
	v_ashrrev_i32_e32 v155, 31, v154
	v_add_f32_e32 v150, 1.0, v150
	v_add_f32_e32 v151, 1.0, v151
	v_rcp_f32_e32 v152, v150
	v_rcp_f32_e32 v153, v151
	v_mul_f32_e32 v151, 0xbfb8aa3b, v126
	v_exp_f32_e32 v151, v151
	v_lshl_add_u32 v150, s44, 8, v144
	v_mul_f32_e32 v124, v124, v152
	v_mul_f32_e32 v125, v125, v153
	v_mul_f32_e32 v152, 0xbfb8aa3b, v127
	v_exp_f32_e32 v152, v152
	v_mul_f32_e32 v116, v124, v116
	v_mul_f32_e32 v117, v125, v117
	v_add_f32_e32 v124, 1.0, v151
	v_mul_f32_e32 v151, 0xbfb8aa3b, v120
	v_add_f32_e32 v125, 1.0, v152
	v_rcp_f32_e32 v124, v124
	v_rcp_f32_e32 v125, v125
	v_exp_f32_e32 v151, v151
	v_mul_f32_e32 v152, 0xbfb8aa3b, v121
	v_exp_f32_e32 v152, v152
	v_mul_f32_e32 v124, v126, v124
	v_mul_f32_e32 v125, v127, v125
	v_add_f32_e32 v126, 1.0, v151
	v_mul_f32_e32 v151, 0xbfb8aa3b, v122
	v_add_f32_e32 v127, 1.0, v152
	v_exp_f32_e32 v151, v151
	v_mul_f32_e32 v152, 0xbfb8aa3b, v123
	v_exp_f32_e32 v153, v152
	v_rcp_f32_e32 v126, v126
	v_add_f32_e32 v151, 1.0, v151
	v_rcp_f32_e32 v127, v127
	v_rcp_f32_e32 v152, v151
	v_add_f32_e32 v151, 1.0, v153
	v_rcp_f32_e32 v153, v151
	v_mul_f32_e32 v120, v120, v126
	v_mul_f32_e32 v121, v121, v127
	v_mul_f32_e32 v118, v124, v118
	v_mul_f32_e32 v119, v125, v119
	v_mul_f32_e32 v112, v120, v112
	v_mul_f32_e32 v113, v121, v113
	v_mul_f32_e32 v120, v122, v152
	v_mul_f32_e32 v121, v123, v153
	v_cvt_pk_bf16_f32 v116, v116, v117
	v_mul_f32_e32 v114, v120, v114
	v_mul_f32_e32 v115, v121, v115
	v_cvt_pk_bf16_f32 v117, v118, v119
	v_cvt_pk_bf16_f32 v119, v114, v115
	v_mul_f32_e32 v114, 0xbfb8aa3b, v108
	v_exp_f32_e32 v114, v114
	v_mul_f32_e32 v115, 0xbfb8aa3b, v109
	v_exp_f32_e32 v115, v115
	v_cvt_pk_bf16_f32 v118, v112, v113
	v_add_f32_e32 v114, 1.0, v114
	v_mov_b64_e32 v[112:113], s[52:53]
	v_rcp_f32_e32 v122, v114
	v_add_f32_e32 v114, 1.0, v115
	v_mad_i64_i32 v[120:121], s[44:45], v150, s30, v[112:113]
	v_rcp_f32_e32 v123, v114
	v_lshlrev_b64 v[114:115], 1, v[154:155]
	v_lshl_add_u64 v[120:121], v[120:121], 0, v[114:115]
	global_store_dwordx4 v[120:121], v[116:119], off
	v_mul_f32_e32 v108, v108, v122
	v_mul_f32_e32 v109, v109, v123
	s_andn2_b64 vcc, exec, s[4:5]
	v_mul_f32_e32 v116, 0xbfb8aa3b, v110
	v_mul_f32_e32 v117, 0xbfb8aa3b, v111
	v_exp_f32_e32 v116, v116
	v_exp_f32_e32 v117, v117
	v_mul_f32_e32 v100, v108, v100
	v_mul_f32_e32 v101, v109, v101
	s_mov_b64 s[4:5], -1
	v_add_f32_e32 v108, 1.0, v116
	v_add_f32_e32 v109, 1.0, v117
	v_mul_f32_e32 v116, 0xbfb8aa3b, v104
	v_mul_f32_e32 v117, 0xbfb8aa3b, v105
	v_rcp_f32_e32 v108, v108
	v_rcp_f32_e32 v109, v109
	v_exp_f32_e32 v116, v116
	v_exp_f32_e32 v117, v117
	v_mul_f32_e32 v108, v110, v108
	v_mul_f32_e32 v109, v111, v109
	v_add_f32_e32 v110, 1.0, v116
	v_add_f32_e32 v111, 1.0, v117
	v_mul_f32_e32 v116, 0xbfb8aa3b, v106
	v_mul_f32_e32 v117, 0xbfb8aa3b, v107
	v_exp_f32_e32 v116, v116
	v_exp_f32_e32 v117, v117
	v_rcp_f32_e32 v110, v110
	v_rcp_f32_e32 v111, v111
	v_add_f32_e32 v116, 1.0, v116
	v_add_f32_e32 v117, 1.0, v117
	v_rcp_f32_e32 v116, v116
	v_rcp_f32_e32 v117, v117
	v_mul_f32_e32 v104, v104, v110
	v_mul_f32_e32 v105, v105, v111
	v_mul_f32_e32 v102, v108, v102
	v_mul_f32_e32 v103, v109, v103
	v_mul_f32_e32 v104, v104, v96
	v_mul_f32_e32 v105, v105, v97
	v_mul_f32_e32 v96, v106, v116
	v_mul_f32_e32 v97, v107, v117
	v_or_b32_e32 v108, 16, v150
	v_mul_f32_e32 v106, v96, v98
	v_mul_f32_e32 v107, v97, v99
	v_mul_f32_e32 v99, 0xbfb8aa3b, v92
	v_cvt_pk_bf16_f32 v96, v100, v101
	v_exp_f32_e32 v100, v99
	v_mul_f32_e32 v99, 0xbfb8aa3b, v93
	v_exp_f32_e32 v101, v99
	v_cvt_pk_bf16_f32 v97, v102, v103
	v_mad_i64_i32 v[102:103], s[44:45], v108, s30, v[112:113]
	v_cvt_pk_bf16_f32 v98, v104, v105
	v_cvt_pk_bf16_f32 v99, v106, v107
	v_add_f32_e32 v100, 1.0, v100
	v_add_f32_e32 v101, 1.0, v101
	v_lshl_add_u64 v[102:103], v[102:103], 0, v[114:115]
	v_rcp_f32_e32 v100, v100
	v_rcp_f32_e32 v101, v101
	global_store_dwordx4 v[102:103], v[96:99], off
	v_mul_f32_e32 v92, v92, v100
	v_mul_f32_e32 v93, v93, v101
	s_nop 0
	v_mul_f32_e32 v96, 0xbfb8aa3b, v94
	v_mul_f32_e32 v97, 0xbfb8aa3b, v95
	v_exp_f32_e32 v96, v96
	v_exp_f32_e32 v97, v97
	v_mul_f32_e32 v84, v92, v84
	v_mul_f32_e32 v85, v93, v85
	v_add_f32_e32 v92, 1.0, v96
	v_add_f32_e32 v93, 1.0, v97
	v_mul_f32_e32 v96, 0xbfb8aa3b, v88
	v_mul_f32_e32 v97, 0xbfb8aa3b, v89
	v_rcp_f32_e32 v92, v92
	v_rcp_f32_e32 v93, v93
	v_exp_f32_e32 v96, v96
	v_exp_f32_e32 v97, v97
	v_mul_f32_e32 v92, v94, v92
	v_mul_f32_e32 v93, v95, v93
	v_add_f32_e32 v94, 1.0, v96
	v_add_f32_e32 v95, 1.0, v97
	v_mul_f32_e32 v96, 0xbfb8aa3b, v90
	v_mul_f32_e32 v97, 0xbfb8aa3b, v91
	v_exp_f32_e32 v96, v96
	v_exp_f32_e32 v97, v97
	v_rcp_f32_e32 v94, v94
	v_rcp_f32_e32 v95, v95
	v_add_f32_e32 v96, 1.0, v96
	v_add_f32_e32 v97, 1.0, v97
	v_rcp_f32_e32 v96, v96
	v_rcp_f32_e32 v97, v97
	v_mul_f32_e32 v88, v88, v94
	v_mul_f32_e32 v89, v89, v95
	v_mul_f32_e32 v86, v92, v86
	v_mul_f32_e32 v87, v93, v87
	v_mul_f32_e32 v88, v88, v80
	v_mul_f32_e32 v89, v89, v81
	v_mul_f32_e32 v80, v90, v96
	v_mul_f32_e32 v81, v91, v97
	v_or_b32_e32 v92, 32, v150
	v_mul_f32_e32 v90, v80, v82
	v_mul_f32_e32 v91, v81, v83
	v_mul_f32_e32 v83, 0xbfb8aa3b, v76
	v_cvt_pk_bf16_f32 v80, v84, v85
	v_exp_f32_e32 v84, v83
	v_mul_f32_e32 v83, 0xbfb8aa3b, v77
	v_exp_f32_e32 v85, v83
	v_cvt_pk_bf16_f32 v81, v86, v87
	v_mad_i64_i32 v[86:87], s[44:45], v92, s30, v[112:113]
	v_cvt_pk_bf16_f32 v82, v88, v89
	v_cvt_pk_bf16_f32 v83, v90, v91
	v_add_f32_e32 v84, 1.0, v84
	v_add_f32_e32 v85, 1.0, v85
; __device__ __forceinline__ unsigned pk2(float lo, float hi) { f32x2 v = {lo, hi}; bf16x2_t b = __builtin_convertvector(v, bf16x2_t); return __builtin_bit_cast(unsigned, b); }
;     __device__ __forceinline__ void operator()(const AccT& acc, const pg8::Unit& u, int wr, int wc, int fr, int fq) const {
;         const int col = u.pn * 128 + wc * 32 + fq * 8;
; #pragma unroll
;         for (int ai = 0; ai < 2; ++ai)
; #pragma unroll
;             for (int m = 0; m < 4; ++m) {
;                 const int row = u.pm * 256 + ai * 128 + wr * 64 + m * 16 + fr;
;                 float o[8];
; #pragma unroll
;                 for (int n = 0; n < 2; ++n)
; #pragma unroll
;                     for (int j = 0; j < 4; ++j) { const float gt = acc[ai][0][m][n][j], up = acc[ai][1][m][n][j];
;                         const float sg = gt * __builtin_amdgcn_rcpf(1.f + __builtin_amdgcn_exp2f(-gt * 1.4426950408889634f)); o[n * 4 + j] = sg * up; }
;                 u32x4 w; w.x = pk2(o[0], o[1]); w.y = pk2(o[2], o[3]); w.z = pk2(o[4], o[5]); w.w = pk2(o[6], o[7]);
;                 *(u32x4*)(H + (size_t)row * DFF + col) = w;
;             }
	v_lshl_add_u64 v[86:87], v[86:87], 0, v[114:115]
	v_rcp_f32_e32 v84, v84
	v_rcp_f32_e32 v85, v85
	global_store_dwordx4 v[86:87], v[80:83], off
	v_mul_f32_e32 v76, v76, v84
	v_mul_f32_e32 v77, v77, v85
	s_nop 0
	v_mul_f32_e32 v80, 0xbfb8aa3b, v78
	v_mul_f32_e32 v81, 0xbfb8aa3b, v79
	v_exp_f32_e32 v80, v80
	v_exp_f32_e32 v81, v81
	v_mul_f32_e32 v68, v76, v68
	v_mul_f32_e32 v69, v77, v69
	v_add_f32_e32 v76, 1.0, v80
	v_add_f32_e32 v77, 1.0, v81
	v_mul_f32_e32 v80, 0xbfb8aa3b, v72
	v_mul_f32_e32 v81, 0xbfb8aa3b, v73
	v_rcp_f32_e32 v76, v76
	v_rcp_f32_e32 v77, v77
	v_exp_f32_e32 v80, v80
	v_exp_f32_e32 v81, v81
	v_mul_f32_e32 v76, v78, v76
	v_mul_f32_e32 v77, v79, v77
	v_add_f32_e32 v78, 1.0, v80
	v_add_f32_e32 v79, 1.0, v81
	v_mul_f32_e32 v80, 0xbfb8aa3b, v74
	v_mul_f32_e32 v81, 0xbfb8aa3b, v75
	v_exp_f32_e32 v80, v80
	v_exp_f32_e32 v81, v81
	v_rcp_f32_e32 v78, v78
	v_rcp_f32_e32 v79, v79
	v_add_f32_e32 v80, 1.0, v80
	v_add_f32_e32 v81, 1.0, v81
	v_rcp_f32_e32 v80, v80
	v_rcp_f32_e32 v81, v81
	v_mul_f32_e32 v72, v72, v78
	v_mul_f32_e32 v73, v73, v79
	v_mul_f32_e32 v70, v76, v70
	v_mul_f32_e32 v71, v77, v71
	v_mul_f32_e32 v72, v72, v64
	v_mul_f32_e32 v73, v73, v65
	v_mul_f32_e32 v64, v74, v80
	v_mul_f32_e32 v65, v75, v81
	v_or_b32_e32 v76, 48, v150
	v_mul_f32_e32 v74, v64, v66
	v_mul_f32_e32 v75, v65, v67
	v_cvt_pk_bf16_f32 v64, v68, v69
	v_mul_f32_e32 v68, 0xbfb8aa3b, v60
	v_cvt_pk_bf16_f32 v65, v70, v71
	v_exp_f32_e32 v70, v68
	v_mul_f32_e32 v68, 0xbfb8aa3b, v61
	v_exp_f32_e32 v71, v68
	v_mad_i64_i32 v[68:69], s[44:45], v76, s30, v[112:113]
	v_cvt_pk_bf16_f32 v66, v72, v73
	v_cvt_pk_bf16_f32 v67, v74, v75
	v_add_f32_e32 v70, 1.0, v70
	v_add_f32_e32 v71, 1.0, v71
	v_lshl_add_u64 v[68:69], v[68:69], 0, v[114:115]
	v_rcp_f32_e32 v70, v70
	v_rcp_f32_e32 v71, v71
	global_store_dwordx4 v[68:69], v[64:67], off
	v_mul_f32_e32 v60, v60, v70
	v_mul_f32_e32 v61, v61, v71
	s_nop 0
	v_mul_f32_e32 v64, 0xbfb8aa3b, v62
	v_mul_f32_e32 v65, 0xbfb8aa3b, v63
	v_exp_f32_e32 v64, v64
	v_exp_f32_e32 v65, v65
	v_mul_f32_e32 v52, v60, v52
	v_mul_f32_e32 v53, v61, v53
	v_add_u32_e32 v66, 0x80, v150
	v_add_f32_e32 v60, 1.0, v64
	v_add_f32_e32 v61, 1.0, v65
	v_mul_f32_e32 v64, 0xbfb8aa3b, v56
	v_mul_f32_e32 v65, 0xbfb8aa3b, v57
	v_rcp_f32_e32 v60, v60
	v_rcp_f32_e32 v61, v61
	v_exp_f32_e32 v64, v64
	v_exp_f32_e32 v65, v65
	v_mul_f32_e32 v60, v62, v60
	v_mul_f32_e32 v61, v63, v61
	v_add_f32_e32 v62, 1.0, v64
	v_add_f32_e32 v63, 1.0, v65
	v_mul_f32_e32 v64, 0xbfb8aa3b, v58
	v_mul_f32_e32 v65, 0xbfb8aa3b, v59
	v_exp_f32_e32 v64, v64
	v_exp_f32_e32 v65, v65
	v_rcp_f32_e32 v62, v62
	v_rcp_f32_e32 v63, v63
	v_add_f32_e32 v64, 1.0, v64
	v_add_f32_e32 v65, 1.0, v65
	v_rcp_f32_e32 v64, v64
	v_rcp_f32_e32 v65, v65
	v_mul_f32_e32 v56, v56, v62
	v_mul_f32_e32 v57, v57, v63
	v_mul_f32_e32 v54, v60, v54
	v_mul_f32_e32 v55, v61, v55
	v_mul_f32_e32 v56, v56, v48
	v_mul_f32_e32 v57, v57, v49
	v_mul_f32_e32 v48, v58, v64
	v_mul_f32_e32 v49, v59, v65
	s_nop 0
	v_mul_f32_e32 v58, v48, v50
	v_mul_f32_e32 v59, v49, v51
	v_mul_f32_e32 v51, 0xbfb8aa3b, v44
	v_cvt_pk_bf16_f32 v48, v52, v53
	v_exp_f32_e32 v52, v51
	v_mul_f32_e32 v51, 0xbfb8aa3b, v45
	v_exp_f32_e32 v53, v51
	v_cvt_pk_bf16_f32 v49, v54, v55
	v_mad_i64_i32 v[54:55], s[44:45], v66, s30, v[112:113]
	v_cvt_pk_bf16_f32 v50, v56, v57
	v_cvt_pk_bf16_f32 v51, v58, v59
	v_add_f32_e32 v52, 1.0, v52
	v_add_f32_e32 v53, 1.0, v53
	v_lshl_add_u64 v[54:55], v[54:55], 0, v[114:115]
	v_rcp_f32_e32 v52, v52
	v_rcp_f32_e32 v53, v53
	global_store_dwordx4 v[54:55], v[48:51], off
	v_mul_f32_e32 v44, v44, v52
	v_mul_f32_e32 v45, v45, v53
	s_nop 0
	v_mul_f32_e32 v48, 0xbfb8aa3b, v46
	v_mul_f32_e32 v49, 0xbfb8aa3b, v47
	v_exp_f32_e32 v48, v48
	v_exp_f32_e32 v49, v49
	v_mul_f32_e32 v36, v44, v36
	v_mul_f32_e32 v37, v45, v37
	v_add_f32_e32 v44, 1.0, v48
	v_add_f32_e32 v45, 1.0, v49
	v_mul_f32_e32 v48, 0xbfb8aa3b, v40
	v_mul_f32_e32 v49, 0xbfb8aa3b, v41
	v_rcp_f32_e32 v44, v44
	v_rcp_f32_e32 v45, v45
	v_exp_f32_e32 v48, v48
	v_exp_f32_e32 v49, v49
	v_mul_f32_e32 v44, v46, v44
	v_mul_f32_e32 v45, v47, v45
	v_add_f32_e32 v46, 1.0, v48
	v_add_f32_e32 v47, 1.0, v49
	v_mul_f32_e32 v48, 0xbfb8aa3b, v42
	v_mul_f32_e32 v49, 0xbfb8aa3b, v43
	v_exp_f32_e32 v48, v48
; __device__ __forceinline__ unsigned pk2(float lo, float hi) { f32x2 v = {lo, hi}; bf16x2_t b = __builtin_convertvector(v, bf16x2_t); return __builtin_bit_cast(unsigned, b); }
;     __device__ __forceinline__ void operator()(const AccT& acc, const pg8::Unit& u, int wr, int wc, int fr, int fq) const {
;         const int col = u.pn * 128 + wc * 32 + fq * 8;
; #pragma unroll
;         for (int ai = 0; ai < 2; ++ai)
; #pragma unroll
;             for (int m = 0; m < 4; ++m) {
;                 const int row = u.pm * 256 + ai * 128 + wr * 64 + m * 16 + fr;
;                 float o[8];
; #pragma unroll
;                 for (int n = 0; n < 2; ++n)
; #pragma unroll
;                     for (int j = 0; j < 4; ++j) { const float gt = acc[ai][0][m][n][j], up = acc[ai][1][m][n][j];
;                         const float sg = gt * __builtin_amdgcn_rcpf(1.f + __builtin_amdgcn_exp2f(-gt * 1.4426950408889634f)); o[n * 4 + j] = sg * up; }
;                 u32x4 w; w.x = pk2(o[0], o[1]); w.y = pk2(o[2], o[3]); w.z = pk2(o[4], o[5]); w.w = pk2(o[6], o[7]);
;                 *(u32x4*)(H + (size_t)row * DFF + col) = w;
;             }
	v_exp_f32_e32 v49, v49
	v_rcp_f32_e32 v46, v46
	v_rcp_f32_e32 v47, v47
	v_add_f32_e32 v48, 1.0, v48
	v_add_f32_e32 v49, 1.0, v49
	v_rcp_f32_e32 v48, v48
	v_rcp_f32_e32 v49, v49
	v_mul_f32_e32 v40, v40, v46
	v_mul_f32_e32 v41, v41, v47
	v_mul_f32_e32 v38, v44, v38
	v_mul_f32_e32 v39, v45, v39
	v_mul_f32_e32 v40, v40, v32
	v_mul_f32_e32 v41, v41, v33
	v_mul_f32_e32 v32, v42, v48
	v_mul_f32_e32 v33, v43, v49
	v_add_u32_e32 v44, 0x90, v150
	v_mul_f32_e32 v42, v32, v34
	v_mul_f32_e32 v43, v33, v35
	v_mul_f32_e32 v35, 0xbfb8aa3b, v28
	v_cvt_pk_bf16_f32 v32, v36, v37
	v_exp_f32_e32 v36, v35
	v_mul_f32_e32 v35, 0xbfb8aa3b, v29
	v_exp_f32_e32 v37, v35
	v_cvt_pk_bf16_f32 v33, v38, v39
	v_mad_i64_i32 v[38:39], s[44:45], v44, s30, v[112:113]
	v_cvt_pk_bf16_f32 v34, v40, v41
	v_cvt_pk_bf16_f32 v35, v42, v43
	v_add_f32_e32 v36, 1.0, v36
	v_add_f32_e32 v37, 1.0, v37
	v_lshl_add_u64 v[38:39], v[38:39], 0, v[114:115]
	v_rcp_f32_e32 v36, v36
	v_rcp_f32_e32 v37, v37
	global_store_dwordx4 v[38:39], v[32:35], off
	v_mul_f32_e32 v28, v28, v36
	v_mul_f32_e32 v29, v29, v37
	s_nop 0
	v_mul_f32_e32 v32, 0xbfb8aa3b, v30
	v_mul_f32_e32 v33, 0xbfb8aa3b, v31
	v_exp_f32_e32 v32, v32
	v_exp_f32_e32 v33, v33
	v_mul_f32_e32 v20, v28, v20
	v_mul_f32_e32 v21, v29, v21
	v_add_f32_e32 v28, 1.0, v32
	v_add_f32_e32 v29, 1.0, v33
	v_mul_f32_e32 v32, 0xbfb8aa3b, v24
	v_mul_f32_e32 v33, 0xbfb8aa3b, v25
	v_rcp_f32_e32 v28, v28
	v_rcp_f32_e32 v29, v29
	v_exp_f32_e32 v32, v32
	v_exp_f32_e32 v33, v33
	v_mul_f32_e32 v28, v30, v28
	v_mul_f32_e32 v29, v31, v29
	v_add_f32_e32 v30, 1.0, v32
	v_add_f32_e32 v31, 1.0, v33
	v_mul_f32_e32 v32, 0xbfb8aa3b, v26
	v_mul_f32_e32 v33, 0xbfb8aa3b, v27
	v_exp_f32_e32 v32, v32
	v_exp_f32_e32 v33, v33
	v_rcp_f32_e32 v30, v30
	v_rcp_f32_e32 v31, v31
	v_add_f32_e32 v32, 1.0, v32
	v_add_f32_e32 v33, 1.0, v33
	v_rcp_f32_e32 v32, v32
	v_rcp_f32_e32 v33, v33
	v_mul_f32_e32 v24, v24, v30
	v_mul_f32_e32 v25, v25, v31
	v_mul_f32_e32 v22, v28, v22
	v_mul_f32_e32 v23, v29, v23
	v_mul_f32_e32 v24, v24, v16
	v_mul_f32_e32 v25, v25, v17
	v_mul_f32_e32 v16, v26, v32
	v_mul_f32_e32 v17, v27, v33
	v_add_u32_e32 v28, 0xa0, v150
	v_mul_f32_e32 v26, v16, v18
	v_mul_f32_e32 v27, v17, v19
	v_mul_f32_e32 v19, 0xbfb8aa3b, v12
	v_cvt_pk_bf16_f32 v16, v20, v21
	v_exp_f32_e32 v20, v19
	v_mul_f32_e32 v19, 0xbfb8aa3b, v13
	v_exp_f32_e32 v21, v19
	v_cvt_pk_bf16_f32 v17, v22, v23
	v_mad_i64_i32 v[22:23], s[44:45], v28, s30, v[112:113]
	v_cvt_pk_bf16_f32 v18, v24, v25
	v_cvt_pk_bf16_f32 v19, v26, v27
	v_add_f32_e32 v20, 1.0, v20
	v_add_f32_e32 v21, 1.0, v21
	v_lshl_add_u64 v[22:23], v[22:23], 0, v[114:115]
	v_rcp_f32_e32 v20, v20
	v_rcp_f32_e32 v21, v21
	global_store_dwordx4 v[22:23], v[16:19], off
	v_mul_f32_e32 v12, v12, v20
	v_mul_f32_e32 v13, v13, v21
	s_nop 0
	v_mul_f32_e32 v16, 0xbfb8aa3b, v14
	v_mul_f32_e32 v17, 0xbfb8aa3b, v15
	v_exp_f32_e32 v16, v16
	v_exp_f32_e32 v17, v17
	v_mul_f32_e32 v4, v12, v4
	v_mul_f32_e32 v5, v13, v5
	v_add_f32_e32 v12, 1.0, v16
	v_add_f32_e32 v13, 1.0, v17
	v_mul_f32_e32 v16, 0xbfb8aa3b, v8
	v_mul_f32_e32 v17, 0xbfb8aa3b, v9
	v_rcp_f32_e32 v12, v12
	v_rcp_f32_e32 v13, v13
	v_exp_f32_e32 v16, v16
	v_exp_f32_e32 v17, v17
	v_mul_f32_e32 v12, v14, v12
	v_mul_f32_e32 v13, v15, v13
	v_add_f32_e32 v14, 1.0, v16
	v_add_f32_e32 v15, 1.0, v17
	v_mul_f32_e32 v16, 0xbfb8aa3b, v10
	v_mul_f32_e32 v17, 0xbfb8aa3b, v11
	v_exp_f32_e32 v16, v16
	v_exp_f32_e32 v17, v17
	v_rcp_f32_e32 v14, v14
	v_rcp_f32_e32 v15, v15
	v_add_f32_e32 v16, 1.0, v16
	v_add_f32_e32 v17, 1.0, v17
	v_rcp_f32_e32 v16, v16
	v_rcp_f32_e32 v17, v17
	v_mul_f32_e32 v8, v8, v14
	v_mul_f32_e32 v9, v9, v15
	v_mul_f32_e32 v6, v12, v6
	v_mul_f32_e32 v7, v13, v7
	v_mul_f32_e32 v8, v8, v0
	v_mul_f32_e32 v9, v9, v1
	v_mul_f32_e32 v0, v10, v16
	v_mul_f32_e32 v1, v11, v17
	v_add_u32_e32 v12, 0xb0, v150
	v_mul_f32_e32 v10, v0, v2
	v_mul_f32_e32 v11, v1, v3
	v_cvt_pk_bf16_f32 v0, v4, v5
	v_mad_i64_i32 v[4:5], s[44:45], v12, s30, v[112:113]
	v_cvt_pk_bf16_f32 v1, v6, v7
	v_cvt_pk_bf16_f32 v2, v8, v9
	v_cvt_pk_bf16_f32 v3, v10, v11
	v_lshl_add_u64 v[4:5], v[4:5], 0, v[114:115]
	global_store_dwordx4 v[4:5], v[0:3], off
	s_cbranch_vccnz .LBB0_578
	s_andn2_b64 vcc, exec, s[8:9]
	s_cbranch_vccnz .LBB0_577
	s_barrier
	s_branch .LBB0_577

; __device__ __forceinline__ unsigned pk2(float lo, float hi) { f32x2 v = {lo, hi}; bf16x2_t b = __builtin_convertvector(v, bf16x2_t); return __builtin_bit_cast(unsigned, b); }
;     __device__ __forceinline__ void operator()(const AccT& acc, const pg8::Unit& u, int wr, int wc, int fr, int fq) const {
;         const int col = u.pn * 128 + wc * 32 + fq * 8;
; #pragma unroll
;         for (int ai = 0; ai < 2; ++ai)
; #pragma unroll
;             for (int m = 0; m < 4; ++m) {
;                 const int row = u.pm * 256 + ai * 128 + wr * 64 + m * 16 + fr;
;                 float o[8];
; #pragma unroll
;                 for (int n = 0; n < 2; ++n)
; #pragma unroll
;                     for (int j = 0; j < 4; ++j) { const float gt = acc[ai][0][m][n][j], up = acc[ai][1][m][n][j];
;                         const float sg = gt * __builtin_amdgcn_rcpf(1.f + __builtin_amdgcn_exp2f(-gt * 1.4426950408889634f)); o[n * 4 + j] = sg * up; }
;                 u32x4 w; w.x = pk2(o[0], o[1]); w.y = pk2(o[2], o[3]); w.z = pk2(o[4], o[5]); w.w = pk2(o[6], o[7]);
;                 *(u32x4*)(H + (size_t)row * DFF + col) = w;
;             }
.LBB0_1587:
	v_mul_f32_e32 v150, 0xbfb8aa3b, v124
	v_mul_f32_e32 v151, 0xbfb8aa3b, v125
	v_exp_f32_e32 v150, v150
	v_exp_f32_e32 v151, v151
	v_lshl_or_b32 v154, s49, 7, v146
	v_ashrrev_i32_e32 v155, 31, v154
	v_add_f32_e32 v150, 1.0, v150
	v_add_f32_e32 v151, 1.0, v151
	v_rcp_f32_e32 v152, v150
	v_rcp_f32_e32 v153, v151
	v_mul_f32_e32 v151, 0xbfb8aa3b, v126
	v_exp_f32_e32 v151, v151
	v_lshl_add_u32 v150, s22, 8, v144
	v_mul_f32_e32 v124, v124, v152
	v_mul_f32_e32 v125, v125, v153
	v_mul_f32_e32 v152, 0xbfb8aa3b, v127
	v_exp_f32_e32 v152, v152
	v_mul_f32_e32 v116, v124, v116
	v_mul_f32_e32 v117, v125, v117
	v_add_f32_e32 v124, 1.0, v151
	v_mul_f32_e32 v151, 0xbfb8aa3b, v120
	v_add_f32_e32 v125, 1.0, v152
	v_rcp_f32_e32 v124, v124
	v_rcp_f32_e32 v125, v125
	v_exp_f32_e32 v151, v151
	v_mul_f32_e32 v152, 0xbfb8aa3b, v121
	v_exp_f32_e32 v152, v152
	v_mul_f32_e32 v124, v126, v124
	v_mul_f32_e32 v125, v127, v125
	v_add_f32_e32 v126, 1.0, v151
	v_mul_f32_e32 v151, 0xbfb8aa3b, v122
	v_add_f32_e32 v127, 1.0, v152
	v_exp_f32_e32 v151, v151
	v_mul_f32_e32 v152, 0xbfb8aa3b, v123
	v_exp_f32_e32 v153, v152
	v_rcp_f32_e32 v126, v126
	v_add_f32_e32 v151, 1.0, v151
	v_rcp_f32_e32 v127, v127
	v_rcp_f32_e32 v152, v151
	v_add_f32_e32 v151, 1.0, v153
	v_rcp_f32_e32 v153, v151
	v_mul_f32_e32 v120, v120, v126
	v_mul_f32_e32 v121, v121, v127
	v_mul_f32_e32 v118, v124, v118
	v_mul_f32_e32 v119, v125, v119
	v_mul_f32_e32 v112, v120, v112
	v_mul_f32_e32 v113, v121, v113
	v_mul_f32_e32 v120, v122, v152
	v_mul_f32_e32 v121, v123, v153
	v_cvt_pk_bf16_f32 v116, v116, v117
	v_mul_f32_e32 v114, v120, v114
	v_mul_f32_e32 v115, v121, v115
	v_cvt_pk_bf16_f32 v117, v118, v119
	v_cvt_pk_bf16_f32 v119, v114, v115
	v_mul_f32_e32 v114, 0xbfb8aa3b, v108
	v_exp_f32_e32 v114, v114
	v_mul_f32_e32 v115, 0xbfb8aa3b, v109
	v_exp_f32_e32 v115, v115
	v_cvt_pk_bf16_f32 v118, v112, v113
	v_add_f32_e32 v114, 1.0, v114
	v_mov_b64_e32 v[112:113], s[52:53]
	v_rcp_f32_e32 v122, v114
	v_add_f32_e32 v114, 1.0, v115
	v_mad_i64_i32 v[120:121], s[24:25], v150, s48, v[112:113]
	v_rcp_f32_e32 v123, v114
	v_lshlrev_b64 v[114:115], 1, v[154:155]
	v_lshl_add_u64 v[120:121], v[120:121], 0, v[114:115]
	global_store_dwordx4 v[120:121], v[116:119], off
	v_mul_f32_e32 v108, v108, v122
	v_mul_f32_e32 v109, v109, v123
	s_andn2_b64 vcc, exec, s[4:5]
	v_mul_f32_e32 v116, 0xbfb8aa3b, v110
	v_mul_f32_e32 v117, 0xbfb8aa3b, v111
	v_exp_f32_e32 v116, v116
	v_exp_f32_e32 v117, v117
	v_mul_f32_e32 v100, v108, v100
	v_mul_f32_e32 v101, v109, v101
	s_mov_b64 s[4:5], -1
	v_add_f32_e32 v108, 1.0, v116
	v_add_f32_e32 v109, 1.0, v117
	v_mul_f32_e32 v116, 0xbfb8aa3b, v104
	v_mul_f32_e32 v117, 0xbfb8aa3b, v105
	v_rcp_f32_e32 v108, v108
	v_rcp_f32_e32 v109, v109
	v_exp_f32_e32 v116, v116
	v_exp_f32_e32 v117, v117
	v_mul_f32_e32 v108, v110, v108
	v_mul_f32_e32 v109, v111, v109
	v_add_f32_e32 v110, 1.0, v116
	v_add_f32_e32 v111, 1.0, v117
	v_mul_f32_e32 v116, 0xbfb8aa3b, v106
	v_mul_f32_e32 v117, 0xbfb8aa3b, v107
	v_exp_f32_e32 v116, v116
	v_exp_f32_e32 v117, v117
	v_rcp_f32_e32 v110, v110
	v_rcp_f32_e32 v111, v111
	v_add_f32_e32 v116, 1.0, v116
	v_add_f32_e32 v117, 1.0, v117
	v_rcp_f32_e32 v116, v116
	v_rcp_f32_e32 v117, v117
	v_mul_f32_e32 v104, v104, v110
	v_mul_f32_e32 v105, v105, v111
	v_mul_f32_e32 v102, v108, v102
	v_mul_f32_e32 v103, v109, v103
	v_mul_f32_e32 v104, v104, v96
	v_mul_f32_e32 v105, v105, v97
	v_mul_f32_e32 v96, v106, v116
	v_mul_f32_e32 v97, v107, v117
	v_or_b32_e32 v108, 16, v150
	v_mul_f32_e32 v106, v96, v98
	v_mul_f32_e32 v107, v97, v99
	v_mul_f32_e32 v99, 0xbfb8aa3b, v92
	v_cvt_pk_bf16_f32 v96, v100, v101
	v_exp_f32_e32 v100, v99
	v_mul_f32_e32 v99, 0xbfb8aa3b, v93
	v_exp_f32_e32 v101, v99
	v_cvt_pk_bf16_f32 v97, v102, v103
	v_mad_i64_i32 v[102:103], s[24:25], v108, s48, v[112:113]
	v_cvt_pk_bf16_f32 v98, v104, v105
	v_cvt_pk_bf16_f32 v99, v106, v107
	v_add_f32_e32 v100, 1.0, v100
	v_add_f32_e32 v101, 1.0, v101
	v_lshl_add_u64 v[102:103], v[102:103], 0, v[114:115]
	v_rcp_f32_e32 v100, v100
	v_rcp_f32_e32 v101, v101
	global_store_dwordx4 v[102:103], v[96:99], off
	v_mul_f32_e32 v92, v92, v100
	v_mul_f32_e32 v93, v93, v101
	s_nop 0
	v_mul_f32_e32 v96, 0xbfb8aa3b, v94
	v_mul_f32_e32 v97, 0xbfb8aa3b, v95
	v_exp_f32_e32 v96, v96
	v_exp_f32_e32 v97, v97
	v_mul_f32_e32 v84, v92, v84
	v_mul_f32_e32 v85, v93, v85
	v_add_f32_e32 v92, 1.0, v96
	v_add_f32_e32 v93, 1.0, v97
	v_mul_f32_e32 v96, 0xbfb8aa3b, v88
	v_mul_f32_e32 v97, 0xbfb8aa3b, v89
	v_rcp_f32_e32 v92, v92
	v_rcp_f32_e32 v93, v93
	v_exp_f32_e32 v96, v96
	v_exp_f32_e32 v97, v97
	v_mul_f32_e32 v92, v94, v92
	v_mul_f32_e32 v93, v95, v93
	v_add_f32_e32 v94, 1.0, v96
	v_add_f32_e32 v95, 1.0, v97
	v_mul_f32_e32 v96, 0xbfb8aa3b, v90
	v_mul_f32_e32 v97, 0xbfb8aa3b, v91
	v_exp_f32_e32 v96, v96
	v_exp_f32_e32 v97, v97
	v_rcp_f32_e32 v94, v94
	v_rcp_f32_e32 v95, v95
	v_add_f32_e32 v96, 1.0, v96
	v_add_f32_e32 v97, 1.0, v97
	v_rcp_f32_e32 v96, v96
	v_rcp_f32_e32 v97, v97
	v_mul_f32_e32 v88, v88, v94
	v_mul_f32_e32 v89, v89, v95
	v_mul_f32_e32 v86, v92, v86
	v_mul_f32_e32 v87, v93, v87
	v_mul_f32_e32 v88, v88, v80
	v_mul_f32_e32 v89, v89, v81
	v_mul_f32_e32 v80, v90, v96
	v_mul_f32_e32 v81, v91, v97
	v_or_b32_e32 v92, 32, v150
	v_mul_f32_e32 v90, v80, v82
	v_mul_f32_e32 v91, v81, v83
	v_mul_f32_e32 v83, 0xbfb8aa3b, v76
	v_cvt_pk_bf16_f32 v80, v84, v85
	v_exp_f32_e32 v84, v83
	v_mul_f32_e32 v83, 0xbfb8aa3b, v77
	v_exp_f32_e32 v85, v83
	v_cvt_pk_bf16_f32 v81, v86, v87
	v_mad_i64_i32 v[86:87], s[24:25], v92, s48, v[112:113]
	v_cvt_pk_bf16_f32 v82, v88, v89
	v_cvt_pk_bf16_f32 v83, v90, v91
	v_add_f32_e32 v84, 1.0, v84
	v_add_f32_e32 v85, 1.0, v85
; __device__ __forceinline__ unsigned pk2(float lo, float hi) { f32x2 v = {lo, hi}; bf16x2_t b = __builtin_convertvector(v, bf16x2_t); return __builtin_bit_cast(unsigned, b); }
;     __device__ __forceinline__ void operator()(const AccT& acc, const pg8::Unit& u, int wr, int wc, int fr, int fq) const {
;         const int col = u.pn * 128 + wc * 32 + fq * 8;
; #pragma unroll
;         for (int ai = 0; ai < 2; ++ai)
; #pragma unroll
;             for (int m = 0; m < 4; ++m) {
;                 const int row = u.pm * 256 + ai * 128 + wr * 64 + m * 16 + fr;
;                 float o[8];
; #pragma unroll
;                 for (int n = 0; n < 2; ++n)
; #pragma unroll
;                     for (int j = 0; j < 4; ++j) { const float gt = acc[ai][0][m][n][j], up = acc[ai][1][m][n][j];
;                         const float sg = gt * __builtin_amdgcn_rcpf(1.f + __builtin_amdgcn_exp2f(-gt * 1.4426950408889634f)); o[n * 4 + j] = sg * up; }
;                 u32x4 w; w.x = pk2(o[0], o[1]); w.y = pk2(o[2], o[3]); w.z = pk2(o[4], o[5]); w.w = pk2(o[6], o[7]);
;                 *(u32x4*)(H + (size_t)row * DFF + col) = w;
;             }
	v_lshl_add_u64 v[86:87], v[86:87], 0, v[114:115]
	v_rcp_f32_e32 v84, v84
	v_rcp_f32_e32 v85, v85
	global_store_dwordx4 v[86:87], v[80:83], off
	v_mul_f32_e32 v76, v76, v84
	v_mul_f32_e32 v77, v77, v85
	s_nop 0
	v_mul_f32_e32 v80, 0xbfb8aa3b, v78
	v_mul_f32_e32 v81, 0xbfb8aa3b, v79
	v_exp_f32_e32 v80, v80
	v_exp_f32_e32 v81, v81
	v_mul_f32_e32 v68, v76, v68
	v_mul_f32_e32 v69, v77, v69
	v_add_f32_e32 v76, 1.0, v80
	v_add_f32_e32 v77, 1.0, v81
	v_mul_f32_e32 v80, 0xbfb8aa3b, v72
	v_mul_f32_e32 v81, 0xbfb8aa3b, v73
	v_rcp_f32_e32 v76, v76
	v_rcp_f32_e32 v77, v77
	v_exp_f32_e32 v80, v80
	v_exp_f32_e32 v81, v81
	v_mul_f32_e32 v76, v78, v76
	v_mul_f32_e32 v77, v79, v77
	v_add_f32_e32 v78, 1.0, v80
	v_add_f32_e32 v79, 1.0, v81
	v_mul_f32_e32 v80, 0xbfb8aa3b, v74
	v_mul_f32_e32 v81, 0xbfb8aa3b, v75
	v_exp_f32_e32 v80, v80
	v_exp_f32_e32 v81, v81
	v_rcp_f32_e32 v78, v78
	v_rcp_f32_e32 v79, v79
	v_add_f32_e32 v80, 1.0, v80
	v_add_f32_e32 v81, 1.0, v81
	v_rcp_f32_e32 v80, v80
	v_rcp_f32_e32 v81, v81
	v_mul_f32_e32 v72, v72, v78
	v_mul_f32_e32 v73, v73, v79
	v_mul_f32_e32 v70, v76, v70
	v_mul_f32_e32 v71, v77, v71
	v_mul_f32_e32 v72, v72, v64
	v_mul_f32_e32 v73, v73, v65
	v_mul_f32_e32 v64, v74, v80
	v_mul_f32_e32 v65, v75, v81
	v_or_b32_e32 v76, 48, v150
	v_mul_f32_e32 v74, v64, v66
	v_mul_f32_e32 v75, v65, v67
	v_cvt_pk_bf16_f32 v64, v68, v69
	v_mul_f32_e32 v68, 0xbfb8aa3b, v60
	v_cvt_pk_bf16_f32 v65, v70, v71
	v_exp_f32_e32 v70, v68
	v_mul_f32_e32 v68, 0xbfb8aa3b, v61
	v_exp_f32_e32 v71, v68
	v_mad_i64_i32 v[68:69], s[24:25], v76, s48, v[112:113]
	v_cvt_pk_bf16_f32 v66, v72, v73
	v_cvt_pk_bf16_f32 v67, v74, v75
	v_add_f32_e32 v70, 1.0, v70
	v_add_f32_e32 v71, 1.0, v71
	v_lshl_add_u64 v[68:69], v[68:69], 0, v[114:115]
	v_rcp_f32_e32 v70, v70
	v_rcp_f32_e32 v71, v71
	global_store_dwordx4 v[68:69], v[64:67], off
	v_mul_f32_e32 v60, v60, v70
	v_mul_f32_e32 v61, v61, v71
	s_nop 0
	v_mul_f32_e32 v64, 0xbfb8aa3b, v62
	v_mul_f32_e32 v65, 0xbfb8aa3b, v63
	v_exp_f32_e32 v64, v64
	v_exp_f32_e32 v65, v65
	v_mul_f32_e32 v52, v60, v52
	v_mul_f32_e32 v53, v61, v53
	v_add_u32_e32 v66, 0x80, v150
	v_add_f32_e32 v60, 1.0, v64
	v_add_f32_e32 v61, 1.0, v65
	v_mul_f32_e32 v64, 0xbfb8aa3b, v56
	v_mul_f32_e32 v65, 0xbfb8aa3b, v57
	v_rcp_f32_e32 v60, v60
	v_rcp_f32_e32 v61, v61
	v_exp_f32_e32 v64, v64
	v_exp_f32_e32 v65, v65
	v_mul_f32_e32 v60, v62, v60
	v_mul_f32_e32 v61, v63, v61
	v_add_f32_e32 v62, 1.0, v64
	v_add_f32_e32 v63, 1.0, v65
	v_mul_f32_e32 v64, 0xbfb8aa3b, v58
	v_mul_f32_e32 v65, 0xbfb8aa3b, v59
	v_exp_f32_e32 v64, v64
	v_exp_f32_e32 v65, v65
	v_rcp_f32_e32 v62, v62
	v_rcp_f32_e32 v63, v63
	v_add_f32_e32 v64, 1.0, v64
	v_add_f32_e32 v65, 1.0, v65
	v_rcp_f32_e32 v64, v64
	v_rcp_f32_e32 v65, v65
	v_mul_f32_e32 v56, v56, v62
	v_mul_f32_e32 v57, v57, v63
	v_mul_f32_e32 v54, v60, v54
	v_mul_f32_e32 v55, v61, v55
	v_mul_f32_e32 v56, v56, v48
	v_mul_f32_e32 v57, v57, v49
	v_mul_f32_e32 v48, v58, v64
	v_mul_f32_e32 v49, v59, v65
	s_nop 0
	v_mul_f32_e32 v58, v48, v50
	v_mul_f32_e32 v59, v49, v51
	v_mul_f32_e32 v51, 0xbfb8aa3b, v44
	v_cvt_pk_bf16_f32 v48, v52, v53
	v_exp_f32_e32 v52, v51
	v_mul_f32_e32 v51, 0xbfb8aa3b, v45
	v_exp_f32_e32 v53, v51
	v_cvt_pk_bf16_f32 v49, v54, v55
	v_mad_i64_i32 v[54:55], s[24:25], v66, s48, v[112:113]
	v_cvt_pk_bf16_f32 v50, v56, v57
	v_cvt_pk_bf16_f32 v51, v58, v59
	v_add_f32_e32 v52, 1.0, v52
	v_add_f32_e32 v53, 1.0, v53
	v_lshl_add_u64 v[54:55], v[54:55], 0, v[114:115]
	v_rcp_f32_e32 v52, v52
	v_rcp_f32_e32 v53, v53
	global_store_dwordx4 v[54:55], v[48:51], off
	v_mul_f32_e32 v44, v44, v52
	v_mul_f32_e32 v45, v45, v53
	s_nop 0
	v_mul_f32_e32 v48, 0xbfb8aa3b, v46
	v_mul_f32_e32 v49, 0xbfb8aa3b, v47
	v_exp_f32_e32 v48, v48
	v_exp_f32_e32 v49, v49
	v_mul_f32_e32 v36, v44, v36
	v_mul_f32_e32 v37, v45, v37
	v_add_f32_e32 v44, 1.0, v48
	v_add_f32_e32 v45, 1.0, v49
	v_mul_f32_e32 v48, 0xbfb8aa3b, v40
	v_mul_f32_e32 v49, 0xbfb8aa3b, v41
	v_rcp_f32_e32 v44, v44
	v_rcp_f32_e32 v45, v45
	v_exp_f32_e32 v48, v48
	v_exp_f32_e32 v49, v49
	v_mul_f32_e32 v44, v46, v44
	v_mul_f32_e32 v45, v47, v45
	v_add_f32_e32 v46, 1.0, v48
	v_add_f32_e32 v47, 1.0, v49
	v_mul_f32_e32 v48, 0xbfb8aa3b, v42
	v_mul_f32_e32 v49, 0xbfb8aa3b, v43
	v_exp_f32_e32 v48, v48
; __device__ __forceinline__ unsigned pk2(float lo, float hi) { f32x2 v = {lo, hi}; bf16x2_t b = __builtin_convertvector(v, bf16x2_t); return __builtin_bit_cast(unsigned, b); }
;     __device__ __forceinline__ void operator()(const AccT& acc, const pg8::Unit& u, int wr, int wc, int fr, int fq) const {
;         const int col = u.pn * 128 + wc * 32 + fq * 8;
; #pragma unroll
;         for (int ai = 0; ai < 2; ++ai)
; #pragma unroll
;             for (int m = 0; m < 4; ++m) {
;                 const int row = u.pm * 256 + ai * 128 + wr * 64 + m * 16 + fr;
;                 float o[8];
; #pragma unroll
;                 for (int n = 0; n < 2; ++n)
; #pragma unroll
;                     for (int j = 0; j < 4; ++j) { const float gt = acc[ai][0][m][n][j], up = acc[ai][1][m][n][j];
;                         const float sg = gt * __builtin_amdgcn_rcpf(1.f + __builtin_amdgcn_exp2f(-gt * 1.4426950408889634f)); o[n * 4 + j] = sg * up; }
;                 u32x4 w; w.x = pk2(o[0], o[1]); w.y = pk2(o[2], o[3]); w.z = pk2(o[4], o[5]); w.w = pk2(o[6], o[7]);
;                 *(u32x4*)(H + (size_t)row * DFF + col) = w;
;             }
	v_exp_f32_e32 v49, v49
	v_rcp_f32_e32 v46, v46
	v_rcp_f32_e32 v47, v47
	v_add_f32_e32 v48, 1.0, v48
	v_add_f32_e32 v49, 1.0, v49
	v_rcp_f32_e32 v48, v48
	v_rcp_f32_e32 v49, v49
	v_mul_f32_e32 v40, v40, v46
	v_mul_f32_e32 v41, v41, v47
	v_mul_f32_e32 v38, v44, v38
	v_mul_f32_e32 v39, v45, v39
	v_mul_f32_e32 v40, v40, v32
	v_mul_f32_e32 v41, v41, v33
	v_mul_f32_e32 v32, v42, v48
	v_mul_f32_e32 v33, v43, v49
	v_add_u32_e32 v44, 0x90, v150
	v_mul_f32_e32 v42, v32, v34
	v_mul_f32_e32 v43, v33, v35
	v_mul_f32_e32 v35, 0xbfb8aa3b, v28
	v_cvt_pk_bf16_f32 v32, v36, v37
	v_exp_f32_e32 v36, v35
	v_mul_f32_e32 v35, 0xbfb8aa3b, v29
	v_exp_f32_e32 v37, v35
	v_cvt_pk_bf16_f32 v33, v38, v39
	v_mad_i64_i32 v[38:39], s[24:25], v44, s48, v[112:113]
	v_cvt_pk_bf16_f32 v34, v40, v41
	v_cvt_pk_bf16_f32 v35, v42, v43
	v_add_f32_e32 v36, 1.0, v36
	v_add_f32_e32 v37, 1.0, v37
	v_lshl_add_u64 v[38:39], v[38:39], 0, v[114:115]
	v_rcp_f32_e32 v36, v36
	v_rcp_f32_e32 v37, v37
	global_store_dwordx4 v[38:39], v[32:35], off
	v_mul_f32_e32 v28, v28, v36
	v_mul_f32_e32 v29, v29, v37
	s_nop 0
	v_mul_f32_e32 v32, 0xbfb8aa3b, v30
	v_mul_f32_e32 v33, 0xbfb8aa3b, v31
	v_exp_f32_e32 v32, v32
	v_exp_f32_e32 v33, v33
	v_mul_f32_e32 v20, v28, v20
	v_mul_f32_e32 v21, v29, v21
	v_add_f32_e32 v28, 1.0, v32
	v_add_f32_e32 v29, 1.0, v33
	v_mul_f32_e32 v32, 0xbfb8aa3b, v24
	v_mul_f32_e32 v33, 0xbfb8aa3b, v25
	v_rcp_f32_e32 v28, v28
	v_rcp_f32_e32 v29, v29
	v_exp_f32_e32 v32, v32
	v_exp_f32_e32 v33, v33
	v_mul_f32_e32 v28, v30, v28
	v_mul_f32_e32 v29, v31, v29
	v_add_f32_e32 v30, 1.0, v32
	v_add_f32_e32 v31, 1.0, v33
	v_mul_f32_e32 v32, 0xbfb8aa3b, v26
	v_mul_f32_e32 v33, 0xbfb8aa3b, v27
	v_exp_f32_e32 v32, v32
	v_exp_f32_e32 v33, v33
	v_rcp_f32_e32 v30, v30
	v_rcp_f32_e32 v31, v31
	v_add_f32_e32 v32, 1.0, v32
	v_add_f32_e32 v33, 1.0, v33
	v_rcp_f32_e32 v32, v32
	v_rcp_f32_e32 v33, v33
	v_mul_f32_e32 v24, v24, v30
	v_mul_f32_e32 v25, v25, v31
	v_mul_f32_e32 v22, v28, v22
	v_mul_f32_e32 v23, v29, v23
	v_mul_f32_e32 v24, v24, v16
	v_mul_f32_e32 v25, v25, v17
	v_mul_f32_e32 v16, v26, v32
	v_mul_f32_e32 v17, v27, v33
	v_add_u32_e32 v28, 0xa0, v150
	v_mul_f32_e32 v26, v16, v18
	v_mul_f32_e32 v27, v17, v19
	v_mul_f32_e32 v19, 0xbfb8aa3b, v12
	v_cvt_pk_bf16_f32 v16, v20, v21
	v_exp_f32_e32 v20, v19
	v_mul_f32_e32 v19, 0xbfb8aa3b, v13
	v_exp_f32_e32 v21, v19
	v_cvt_pk_bf16_f32 v17, v22, v23
	v_mad_i64_i32 v[22:23], s[24:25], v28, s48, v[112:113]
	v_cvt_pk_bf16_f32 v18, v24, v25
	v_cvt_pk_bf16_f32 v19, v26, v27
	v_add_f32_e32 v20, 1.0, v20
	v_add_f32_e32 v21, 1.0, v21
	v_lshl_add_u64 v[22:23], v[22:23], 0, v[114:115]
	v_rcp_f32_e32 v20, v20
	v_rcp_f32_e32 v21, v21
	global_store_dwordx4 v[22:23], v[16:19], off
	v_mul_f32_e32 v12, v12, v20
	v_mul_f32_e32 v13, v13, v21
	s_nop 0
	v_mul_f32_e32 v16, 0xbfb8aa3b, v14
	v_mul_f32_e32 v17, 0xbfb8aa3b, v15
	v_exp_f32_e32 v16, v16
	v_exp_f32_e32 v17, v17
	v_mul_f32_e32 v4, v12, v4
	v_mul_f32_e32 v5, v13, v5
	v_add_f32_e32 v12, 1.0, v16
	v_add_f32_e32 v13, 1.0, v17
	v_mul_f32_e32 v16, 0xbfb8aa3b, v8
	v_mul_f32_e32 v17, 0xbfb8aa3b, v9
	v_rcp_f32_e32 v12, v12
	v_rcp_f32_e32 v13, v13
	v_exp_f32_e32 v16, v16
	v_exp_f32_e32 v17, v17
	v_mul_f32_e32 v12, v14, v12
	v_mul_f32_e32 v13, v15, v13
	v_add_f32_e32 v14, 1.0, v16
	v_add_f32_e32 v15, 1.0, v17
	v_mul_f32_e32 v16, 0xbfb8aa3b, v10
	v_mul_f32_e32 v17, 0xbfb8aa3b, v11
	v_exp_f32_e32 v16, v16
	v_exp_f32_e32 v17, v17
	v_rcp_f32_e32 v14, v14
	v_rcp_f32_e32 v15, v15
	v_add_f32_e32 v16, 1.0, v16
	v_add_f32_e32 v17, 1.0, v17
	v_rcp_f32_e32 v16, v16
	v_rcp_f32_e32 v17, v17
	v_mul_f32_e32 v8, v8, v14
	v_mul_f32_e32 v9, v9, v15
	v_mul_f32_e32 v6, v12, v6
	v_mul_f32_e32 v7, v13, v7
	v_mul_f32_e32 v8, v8, v0
	v_mul_f32_e32 v9, v9, v1
	v_mul_f32_e32 v0, v10, v16
	v_mul_f32_e32 v1, v11, v17
	v_add_u32_e32 v12, 0xb0, v150
	v_mul_f32_e32 v10, v0, v2
	v_mul_f32_e32 v11, v1, v3
	v_cvt_pk_bf16_f32 v0, v4, v5
	v_mad_i64_i32 v[4:5], s[24:25], v12, s48, v[112:113]
	v_cvt_pk_bf16_f32 v1, v6, v7
	v_cvt_pk_bf16_f32 v2, v8, v9
	v_cvt_pk_bf16_f32 v3, v10, v11
	v_lshl_add_u64 v[4:5], v[4:5], 0, v[114:115]
	global_store_dwordx4 v[4:5], v[0:3], off
	s_cbranch_vccnz .LBB0_1580
	s_andn2_b64 vcc, exec, s[8:9]
	s_cbranch_vccnz .LBB0_1579
	s_barrier
	s_branch .LBB0_1579
